# workgroup stagger at the attention phase entry: group (bx>>5)&7 sleeps 0..7 x 0.5us so the per-unit Q/K0/V0 prologue bursts of different workgroups no longer coincide
# baseline (speedup 1.0000x reference)
; #define PH(n) if constexpr ((PHASE_MASK >> (n)) & 1)
; __global__ void __launch_bounds__(512, 2) fwd_mega(Args a) {
;     ...
;     {
;         PHASE_BASES;
;         if (wave >= 4) __builtin_amdgcn_s_setprio(1);
;         PH(11) for (int L = vcu; L < 8 * 8 * 16; L += G) {
.LBB0_857:
	s_or_b64 exec, exec, s[6:7]
	s_mov_b64 s[10:11], s[14:15]
	s_mov_b64 s[6:7], s[12:13]
	s_waitcnt lgkmcnt(0)
	v_mov_b32_e32 v0, v184
	s_cmpk_gt_u32 s33, 0xff
	s_barrier
	s_lshr_b32 s96, s2, 5
	s_and_b32 s96, s96, 7
.Lp4_stag:
	s_cmp_eq_u32 s96, 0
	s_cbranch_scc1 .Lp4_stag_done
	s_sleep 19
	s_sub_u32 s96, s96, 1
	s_branch .Lp4_stag
.Lp4_stag_done:
	s_cmpk_gt_u32 s33, 0xff
	s_cbranch_scc0 .LBB0_859
	s_setprio 1
